# attention: mask preparation only on the two masked edge tiles; self-max canonicalisations dropped
# speedup vs baseline: 1.0098x; 1.0053x over previous
; DEVI unsigned pk2(float lo, float hi) { f32x2 v = {lo, hi}; bf16x2_t b = __builtin_convertvector(v, bf16x2_t); return __builtin_bit_cast(unsigned, b); }
; DEVI void attn_item(const P& p, int item, char* smem) {
;     ...
;                 float mx = s[0][0];
; #pragma unroll
;                 for (int n = 0; n < 4; ++n)
; #pragma unroll
;                     for (int j = 0; j < 4; ++j) mx = fmaxf(mx, s[n][j]);
;                 mx = rowmax4(mx);
;                 const float mnew = fmaxf(mrow[m], mx);
;                 const float alpha = __builtin_amdgcn_exp2f(mrow[m] - mnew);
;                 mrow[m] = mnew;
;                 float ls = 0.f;
; #pragma unroll
;                 for (int n = 0; n < 4; ++n)
; #pragma unroll
;                     for (int j = 0; j < 4; ++j) { s[n][j] = __builtin_amdgcn_exp2f(s[n][j] - mnew); ls += s[n][j]; }
;                 lrow[m] = lrow[m] * alpha + ls;
; #pragma unroll
;                 for (int nd = 0; nd < 4; ++nd) O[nd][m] *= alpha;
; #pragma unroll
;                 for (int kk = 0; kk < 2; ++kk) {
;                     union { uint4 u; bf16x8 v; } cv;
;                     cv.u.x = pk2(s[2 * kk][0], s[2 * kk][1]); cv.u.y = pk2(s[2 * kk][2], s[2 * kk][3]);
;                     cv.u.z = pk2(s[2 * kk + 1][0], s[2 * kk + 1][1]); cv.u.w = pk2(s[2 * kk + 1][2], s[2 * kk + 1][3]);
;                     Pf[m][kk] = cv.v;
;                 }
;             }
; #pragma unroll
;             for (int nd = 0; nd < 4; ++nd)
; #pragma unroll
;                 for (int kk = 0; kk < 2; ++kk) {
;                     const int row = 16 * nd + fr, x2 = 2 * ((row >> 1) & 7);
;                     const uint2 lo = *(const uint2*)(sV + row * 128 + (((8 * kk + fq) ^ x2) << 3));
;                     const uint2 hi = *(const uint2*)(sV + row * 128 + (((8 * kk + 4 + fq) ^ x2) << 3));
;                     union { uint4 u; bf16x8 v; } cv;
;                     cv.u.x = lo.x; cv.u.y = lo.y; cv.u.z = hi.x; cv.u.w = hi.y;
; #pragma unroll
;                     for (int m = 0; m < 2; ++m) O[nd][m] = __builtin_amdgcn_mfma_f32_16x16x32_bf16(cv.v, Pf[m][kk], O[nd][m], 0, 0, 0);
;                 }
.LBB0_1433:
	v_max3_f32 v91, v160, v86, v87
	v_sub_f32_e32 v0, v78, v91
	v_exp_f32_e32 v78, v0
	v_sub_f32_e32 v79, v79, v91
	v_exp_f32_e32 v79, v79
	v_sub_f32_e32 v80, v80, v91
	v_exp_f32_e32 v80, v80
	v_sub_f32_e32 v81, v81, v91
	v_exp_f32_e32 v81, v81
	v_sub_f32_e32 v74, v74, v91
	v_add_f32_e32 v82, 0, v78
	v_exp_f32_e32 v74, v74
	v_sub_f32_e32 v75, v75, v91
	v_add_f32_e32 v82, v79, v82
	v_exp_f32_e32 v75, v75
	v_sub_f32_e32 v76, v76, v91
	v_add_f32_e32 v82, v80, v82
	v_exp_f32_e32 v76, v76
	v_sub_f32_e32 v77, v77, v91
	v_add_f32_e32 v82, v81, v82
	v_exp_f32_e32 v77, v77
	v_sub_f32_e32 v58, v58, v91
	v_add_f32_e32 v82, v74, v82
	v_exp_f32_e32 v58, v58
	v_sub_f32_e32 v59, v59, v91
	v_add_f32_e32 v82, v75, v82
	v_exp_f32_e32 v59, v59
	v_add_f32_e32 v82, v76, v82
	v_add_f32_e32 v82, v77, v82
	v_add_f32_e32 v82, v58, v82
	v_sub_f32_e32 v50, v50, v91
	v_sub_f32_e32 v51, v51, v91
	v_exp_f32_e32 v83, v50
	v_add_f32_e32 v50, v59, v82
	v_exp_f32_e32 v82, v51
	v_sub_f32_e32 v51, v52, v91
	v_cvt_pk_bf16_f32 v52, v74, v75
	v_max_f32_e32 v74, v70, v71
	v_max3_f32 v74, v74, v72, v73
	v_max3_f32 v74, v74, v62, v63
	v_max3_f32 v74, v74, v64, v65
	v_max3_f32 v74, v74, v54, v55
	v_sub_f32_e32 v60, v60, v91
	v_max3_f32 v74, v74, v56, v57
	v_exp_f32_e32 v60, v60
	v_sub_f32_e32 v61, v61, v91
	v_max3_f32 v74, v74, v66, v67
	v_exp_f32_e32 v61, v61
	v_max3_f32 v74, v74, v68, v69
	v_mov_b32_e32 v75, v74
	s_nop 1
	v_permlane32_swap_b32_e32 v74, v75
	v_add_f32_e32 v50, v60, v50
	v_exp_f32_e32 v84, v51
	v_sub_f32_e32 v51, v53, v91
	v_sub_f32_e32 v0, v160, v91
	v_add_f32_e32 v50, v61, v50
	v_exp_f32_e32 v85, v51
	v_max_f32_e32 v74, v74, v75
	v_add_f32_e32 v50, v83, v50
	v_exp_f32_e32 v0, v0
	v_mov_b32_e32 v75, v74
	v_add_f32_e32 v50, v82, v50
	s_nop 0
	v_permlane16_swap_b32_e32 v74, v75
	v_add_f32_e32 v50, v84, v50
	v_max3_f32 v93, v159, v74, v75
	v_add_f32_e32 v92, v85, v50
	v_sub_f32_e32 v54, v54, v93
	v_fmac_f32_e32 v92, v158, v0
	v_exp_f32_e32 v158, v54
	v_sub_f32_e32 v54, v55, v93
	v_sub_f32_e32 v74, v159, v93
	v_exp_f32_e32 v159, v54
	v_sub_f32_e32 v54, v56, v93
	v_exp_f32_e32 v160, v54
	v_sub_f32_e32 v54, v57, v93
	v_sub_f32_e32 v62, v62, v93
	v_exp_f32_e32 v161, v54
	v_sub_f32_e32 v54, v66, v93
	v_exp_f32_e32 v94, v62
	v_sub_f32_e32 v62, v63, v93
	v_exp_f32_e32 v162, v54
	v_sub_f32_e32 v54, v67, v93
	v_exp_f32_e32 v95, v62
	v_sub_f32_e32 v62, v64, v93
	v_exp_f32_e32 v163, v54
	v_sub_f32_e32 v54, v68, v93
	v_exp_f32_e32 v96, v62
	v_sub_f32_e32 v62, v65, v93
	v_exp_f32_e32 v164, v54
	v_sub_f32_e32 v54, v69, v93
	v_exp_f32_e32 v97, v62
	v_exp_f32_e32 v165, v54
	ds_read2st64_b64 v[54:57], v132 offset0:16 offset1:20
	ds_read2st64_b64 v[62:65], v133 offset0:16 offset1:20
	v_sub_f32_e32 v70, v70, v93
	v_exp_f32_e32 v86, v70
	v_sub_f32_e32 v70, v71, v93
	v_exp_f32_e32 v87, v70
	v_sub_f32_e32 v70, v72, v93
	v_cvt_pk_bf16_f32 v50, v78, v79
	v_cvt_pk_bf16_f32 v51, v80, v81
	v_cvt_pk_bf16_f32 v53, v76, v77
	v_exp_f32_e32 v88, v70
	v_sub_f32_e32 v70, v73, v93
	v_exp_f32_e32 v90, v74
	ds_read2st64_b64 v[74:77], v134 offset0:16 offset1:20
	ds_read2st64_b64 v[78:81], v135 offset0:16 offset1:20
	v_exp_f32_e32 v89, v70
	s_waitcnt lgkmcnt(3)
	v_mov_b32_e32 v70, v54
	v_mov_b32_e32 v71, v55
	s_waitcnt lgkmcnt(2)
	v_mov_b32_e32 v72, v62
	v_mov_b32_e32 v73, v63
	v_mov_b32_e32 v62, v56
	v_mov_b32_e32 v63, v57
	v_pk_mul_f32 v[40:41], v[40:41], v[0:1] op_sel_hi:[1,0]
	v_pk_mul_f32 v[38:39], v[38:39], v[0:1] op_sel_hi:[1,0]
	v_pk_mul_f32 v[44:45], v[44:45], v[0:1] op_sel_hi:[1,0]
	v_pk_mul_f32 v[42:43], v[42:43], v[0:1] op_sel_hi:[1,0]
	v_cvt_pk_bf16_f32 v58, v58, v59
	v_cvt_pk_bf16_f32 v59, v60, v61
	v_cvt_pk_bf16_f32 v60, v83, v82
	v_cvt_pk_bf16_f32 v61, v84, v85
	v_pk_mul_f32 v[16:17], v[16:17], v[90:91] op_sel_hi:[1,0]
	v_pk_mul_f32 v[14:15], v[14:15], v[90:91] op_sel_hi:[1,0]
	v_cvt_pk_bf16_f32 v66, v86, v87
	v_cvt_pk_bf16_f32 v67, v88, v89
	v_cvt_pk_bf16_f32 v68, v94, v95
	v_cvt_pk_bf16_f32 v69, v96, v97
	s_waitcnt lgkmcnt(1)
	v_mov_b32_e32 v82, v74
	v_mov_b32_e32 v83, v75
	s_waitcnt lgkmcnt(0)
	v_mov_b32_e32 v84, v78
	v_mov_b32_e32 v85, v79
	v_pk_mul_f32 v[12:13], v[12:13], v[90:91] op_sel_hi:[1,0]
	v_pk_mul_f32 v[10:11], v[10:11], v[90:91] op_sel_hi:[1,0]
	v_mov_b32_e32 v78, v76
	v_mov_b32_e32 v79, v77
	v_pk_mul_f32 v[48:49], v[48:49], v[0:1] op_sel_hi:[1,0]
	v_pk_mul_f32 v[46:47], v[46:47], v[0:1] op_sel_hi:[1,0]
	v_mfma_f32_16x16x32_bf16 v[38:41], v[70:73], v[50:53], v[38:41]
	v_mul_f32_e64 v20, v20, v0
	v_mul_f32_e64 v21, v21, v0
	v_pk_mul_f32 v[18:19], v[18:19], v[0:1] op_sel_hi:[1,0]
	v_add_f32_e32 v0, 0, v86
	v_mfma_f32_16x16x32_bf16 v[14:17], v[70:73], v[66:69], v[14:17]
	ds_read2st64_b64 v[54:57], v132 offset0:24 offset1:28
	v_add_f32_e32 v0, v87, v0
	v_add_f32_e32 v0, v88, v0
	v_mfma_f32_16x16x32_bf16 v[42:45], v[62:65], v[50:53], v[42:45]
	v_cvt_pk_bf16_f32 v70, v158, v159
	v_cvt_pk_bf16_f32 v71, v160, v161
	v_cvt_pk_bf16_f32 v72, v162, v163
	v_mfma_f32_16x16x32_bf16 v[10:13], v[62:65], v[66:69], v[10:13]
	ds_read2st64_b64 v[62:65], v133 offset0:24 offset1:28
	v_cvt_pk_bf16_f32 v73, v164, v165
	v_add_f32_e32 v0, v89, v0
	v_mfma_f32_16x16x32_bf16 v[38:41], v[82:85], v[58:61], v[38:41]
	v_add_f32_e32 v0, v94, v0
	s_waitcnt lgkmcnt(1)
	v_mov_b32_e32 v74, v54
	v_mov_b32_e32 v75, v55
	v_mfma_f32_16x16x32_bf16 v[14:17], v[82:85], v[70:73], v[14:17]
	ds_read2st64_b64 v[82:85], v135 offset0:24 offset1:28
	s_waitcnt lgkmcnt(1)
	v_mov_b32_e32 v76, v62
	v_mov_b32_e32 v77, v63
	v_mfma_f32_16x16x32_bf16 v[42:45], v[78:81], v[58:61], v[42:45]
	v_add_f32_e32 v0, v95, v0
	v_mov_b32_e32 v62, v56
	v_mov_b32_e32 v63, v57
	v_mfma_f32_16x16x32_bf16 v[10:13], v[78:81], v[70:73], v[10:13]
	ds_read2st64_b64 v[78:81], v134 offset0:24 offset1:28
	v_add_f32_e32 v0, v96, v0
	v_add_f32_e32 v0, v97, v0
	v_add_f32_e32 v0, v158, v0
	v_pk_mul_f32 v[8:9], v[8:9], v[90:91] op_sel_hi:[1,0]
	v_pk_mul_f32 v[6:7], v[6:7], v[90:91] op_sel_hi:[1,0]
	s_waitcnt lgkmcnt(0)
	v_mov_b32_e32 v86, v78
	v_mov_b32_e32 v87, v79
	v_mov_b32_e32 v88, v82
	v_mov_b32_e32 v89, v83
	v_add_f32_e32 v0, v159, v0
	v_pk_mul_f32 v[4:5], v[4:5], v[90:91] op_sel_hi:[1,0]
	v_pk_mul_f32 v[2:3], v[2:3], v[90:91] op_sel_hi:[1,0]
	v_mov_b32_e32 v82, v80
	v_mov_b32_e32 v83, v81
	v_mfma_f32_16x16x32_bf16 v[46:49], v[74:77], v[50:53], v[46:49]
	v_add_f32_e32 v0, v160, v0
	v_add_f32_e32 v0, v161, v0
	v_add_f32_e32 v0, v162, v0
	v_mfma_f32_16x16x32_bf16 v[6:9], v[74:77], v[66:69], v[6:9]
	v_add_f32_e32 v0, v163, v0
	v_add_f32_e32 v0, v164, v0
	v_add_f32_e32 v0, v165, v0
	v_mfma_f32_16x16x32_bf16 v[18:21], v[62:65], v[50:53], v[18:21]
	v_fmac_f32_e32 v0, v139, v90
	v_mov_b32_e32 v159, v93
	v_mov_b32_e32 v160, v91
	v_mfma_f32_16x16x32_bf16 v[2:5], v[62:65], v[66:69], v[2:5]
	v_mov_b32_e32 v139, v0
	v_mov_b32_e32 v158, v92
	v_mfma_f32_16x16x32_bf16 v[46:49], v[86:89], v[58:61], v[46:49]
	v_mfma_f32_16x16x32_bf16 v[6:9], v[86:89], v[70:73], v[6:9]
	v_mfma_f32_16x16x32_bf16 v[18:21], v[82:85], v[58:61], v[18:21]
	v_mfma_f32_16x16x32_bf16 v[2:5], v[82:85], v[70:73], v[2:5]

; DEVI void attn_item(const P& p, int item, char* smem) {
;     ...
;             __syncthreads();
; #pragma unroll
;             for (int i = 0; i < 2; ++i) {
;                 const int row = (tid >> 3) + 32 * i, ch = tid & 7;
;                 const uint4 kv = *(const uint4*)(KB + ((size_t)(b * TPB + tok0 + row)) * 256 + kvh * 64 + ch * 8);
;                 *(uint4*)(sK + row * 128 + ((ch ^ (row & 7)) << 4)) = kv;
;                 const uint4 vv = *(const uint4*)(VT + ((size_t)(b * 256 + kvh * 64 + row)) * TPB + tok0 + ch * 8);
;                 *(uint4*)(sV + row * 128 + ((ch ^ ((row >> 1) & 7)) << 4)) = vv;
;             }
;             __syncthreads();
;             bf16x8 Kf[4][2];
; #pragma unroll
;             for (int n = 0; n < 4; ++n)
; #pragma unroll
;                 for (int kk = 0; kk < 2; ++kk) Kf[n][kk] = *(const bf16x8*)(sK + (16 * n + fr) * 128 + (((kk * 4 + fq) ^ (fr & 7)) << 4));
;             bf16x8 Pf[2][2];
; #pragma unroll
;             for (int m = 0; m < 2; ++m) {
;                 f32x4 s[4];
; #pragma unroll
;                 for (int n = 0; n < 4; ++n) {
;                     s[n] = (f32x4){0.f, 0.f, 0.f, 0.f};
; #pragma unroll
;                     for (int kk = 0; kk < 2; ++kk) s[n] = __builtin_amdgcn_mfma_f32_16x16x32_bf16(Kf[n][kk], Qf[m][kk], s[n], 0, 0, 0);
;                 }
;                 if (lat && (ti == 0 || ti == 4)) {
;                     const int qpos = q0 + mo + 16 * m + fr, kb = tok0 - CTX;
; #pragma unroll
;                     for (int n = 0; n < 4; ++n)
; #pragma unroll
;                         for (int j = 0; j < 4; ++j) {
;                             const int dd = qpos - (kb + 16 * n + 4 * fq + j);
;                             if (dd > 128 || dd < -128) s[n][j] = -1e30f;
;                         }
.Lat_have:
	s_barrier
	v_add_u32_e32 v66, v123, v127
	v_add_u32_e32 v67, v124, v127
	v_add_u32_e32 v68, v123, v129
	v_add_u32_e32 v69, v124, v129
	s_and_b32 s4, s28, 11
	s_cmp_eq_u32 s4, 0
	s_cselect_b64 s[18:19], -1, 0
	s_and_b64 s[18:19], s[2:3], s[18:19]
	s_andn2_b64 vcc, exec, s[18:19]
	s_cbranch_vccnz .Lat_noprep
	v_sub_u32_e32 v0, s30, v140
	v_subrev_u32_e32 v171, s30, v142
	v_subrev_u32_e32 v170, s30, v143
	v_subrev_u32_e32 v168, s30, v144
	v_subrev_u32_e32 v169, s30, v145
	v_subrev_u32_e32 v165, s30, v146
	v_subrev_u32_e32 v162, s30, v147
	v_subrev_u32_e32 v166, s30, v148
	v_subrev_u32_e32 v163, s30, v149
	v_subrev_u32_e32 v167, s30, v150
	v_subrev_u32_e32 v164, s30, v151
	v_subrev_u32_e32 v161, s30, v140
	v_cmp_gt_u32_e64 s[4:5], s38, v0
	v_cmp_lt_u32_e64 s[6:7], s39, v171
	v_cmp_lt_u32_e64 s[8:9], s39, v170
	v_cmp_lt_u32_e64 s[10:11], s39, v168
	v_cmp_lt_u32_e64 s[12:13], s39, v169
	v_cmp_lt_u32_e64 s[14:15], s39, v165
	v_cmp_lt_u32_e64 s[16:17], s39, v162
	v_cmp_lt_u32_e64 s[20:21], s39, v163
	v_cmp_lt_u32_e64 s[22:23], s39, v167
	v_cmp_lt_u32_e64 s[24:25], s39, v164
.Lat_noprep:
	s_waitcnt vmcnt(0)
	ds_write_b128 v66, v[190:193]
	ds_write_b128 v67, v[194:197] offset:8192
	ds_write_b128 v68, v[198:201]
	ds_write_b128 v69, v[202:205] offset:8192
	s_mov_b32 s99, 0
	s_cmp_lt_u32 s28, 8
	s_cbranch_scc0 .Lat_nopf
	s_cmp_gt_u32 s28, 3
	s_cbranch_scc1 .Lat_ctx
	s_add_i32 s100, s47, 64
	s_add_i32 s98, s100, 0xffffff00
	s_cmpk_lt_u32 s98, 0x1000
	s_cbranch_scc0 .Lat_nopf
	s_branch .Lat_issue

; DEVI void attn_item(const P& p, int item, char* smem) {
;     ...
;             for (int m = 0; m < 2; ++m) {
;                 f32x4 s[4];
; #pragma unroll
;                 for (int n = 0; n < 4; ++n) {
;                     s[n] = (f32x4){0.f, 0.f, 0.f, 0.f};
; #pragma unroll
;                     for (int kk = 0; kk < 2; ++kk) s[n] = __builtin_amdgcn_mfma_f32_16x16x32_bf16(Kf[n][kk], Qf[m][kk], s[n], 0, 0, 0);
;                 }
;                 if (lat && (ti == 0 || ti == 4)) {
;                     const int qpos = q0 + mo + 16 * m + fr, kb = tok0 - CTX;
; #pragma unroll
;                     for (int n = 0; n < 4; ++n)
; #pragma unroll
;                         for (int j = 0; j < 4; ++j) {
;                             const int dd = qpos - (kb + 16 * n + 4 * fq + j);
;                             if (dd > 128 || dd < -128) s[n][j] = -1e30f;
;                         }
;                 }
.LBB0_1442:
	v_mfma_f32_16x16x32_bf16 v[70:73], v[70:73], v[30:33], 0
	s_and_b64 vcc, exec, s[2:3]
	v_mfma_f32_16x16x32_bf16 v[70:73], v[94:97], v[34:37], v[70:73]
	v_max_f32_e32 v94, v78, v79
	v_max3_f32 v94, v94, v80, v81
	v_max3_f32 v94, v94, v74, v75
	v_mfma_f32_16x16x32_bf16 v[62:65], v[62:65], v[30:33], 0
	v_max3_f32 v94, v94, v76, v77
	v_max3_f32 v94, v94, v58, v59
	v_max3_f32 v94, v94, v60, v61
	v_mfma_f32_16x16x32_bf16 v[62:65], v[90:93], v[34:37], v[62:65]
	v_max3_f32 v90, v94, v50, v51
	v_max3_f32 v90, v90, v52, v53
	v_mov_b32_e32 v91, v90
	v_mfma_f32_16x16x32_bf16 v[54:57], v[54:57], v[30:33], 0
	s_nop 0
	v_permlane32_swap_b32_e32 v90, v91
	v_mfma_f32_16x16x32_bf16 v[82:85], v[82:85], v[30:33], 0
	v_mfma_f32_16x16x32_bf16 v[54:57], v[86:89], v[34:37], v[54:57]
	v_max_f32_e32 v86, v90, v91
	v_mov_b32_e32 v87, v86
	v_mfma_f32_16x16x32_bf16 v[66:69], v[66:69], v[34:37], v[82:85]
	s_nop 0
	v_permlane16_swap_b32_e32 v86, v87
	s_cbranch_vccnz .LBB0_1433
	s_nop 0
	v_subrev_u32_e32 v82, s30, v141
	v_cmp_gt_u32_e32 vcc, s37, v82
	v_sub_u32_e32 v82, s30, v141
	s_nop 0
	v_cndmask_b32_e32 v70, v70, v136, vcc
	v_cmp_gt_u32_e32 vcc, s38, v82
	v_subrev_u32_e32 v82, s30, v156
	s_nop 0
	v_cndmask_b32_e32 v71, v136, v71, vcc
	v_cmp_lt_u32_e32 vcc, s39, v82
	v_subrev_u32_e32 v82, s30, v157
	s_nop 0
	v_cndmask_b32_e32 v72, v136, v72, vcc
	v_cmp_lt_u32_e32 vcc, s39, v82
	s_nop 1
	v_cndmask_b32_e32 v73, v136, v73, vcc
	v_cmp_lt_u32_e32 vcc, s39, v161
	s_nop 1
	v_cndmask_b32_e32 v62, v136, v62, vcc
	v_cmp_gt_u32_e32 vcc, s38, v0
	s_nop 1
	v_cndmask_b32_e32 v63, v136, v63, vcc
	v_cmp_lt_u32_e32 vcc, s39, v171
	s_nop 1
	v_cndmask_b32_e32 v64, v136, v64, vcc
	v_cmp_lt_u32_e32 vcc, s39, v170
	s_nop 1
	v_cndmask_b32_e32 v65, v136, v65, vcc
	v_cmp_lt_u32_e32 vcc, s39, v168
	s_nop 1
	v_cndmask_b32_e32 v54, v136, v54, vcc
	v_cmp_lt_u32_e32 vcc, s39, v169
	s_nop 1
	v_cndmask_b32_e32 v55, v136, v55, vcc
	v_cmp_lt_u32_e32 vcc, s39, v165
	s_nop 1
	v_cndmask_b32_e32 v56, v136, v56, vcc
	v_cmp_lt_u32_e32 vcc, s39, v162
	s_nop 1
	v_cndmask_b32_e32 v57, v136, v57, vcc
	v_cmp_lt_u32_e32 vcc, s39, v166
	s_nop 1
	v_cndmask_b32_e32 v66, v136, v66, vcc
	v_cmp_lt_u32_e32 vcc, s39, v163
	s_nop 1
	v_cndmask_b32_e32 v67, v136, v67, vcc
	v_cmp_lt_u32_e32 vcc, s39, v167
	s_nop 1
	v_cndmask_b32_e32 v68, v136, v68, vcc
	v_cmp_lt_u32_e32 vcc, s39, v164
	s_nop 1
	v_cndmask_b32_e32 v69, v136, v69, vcc
	s_branch .LBB0_1433
